# v46: v41 with a longer generation-word poll interval (s_sleep 3) for barrier waiters
# speedup vs baseline: 1.0046x; 1.0046x over previous
.Lxb0_wait:
	global_load_dword v248, v253, s[60:61] sc1
	v_add_u32_e32 v252, 1, v252
	s_waitcnt vmcnt(0)
	v_cmp_ge_u32_e32 vcc, v248, v249
	s_cbranch_vccnz .Lxb0_wdone
	v_cmp_gt_u32_e32 vcc, 0x100000, v252
	s_cbranch_vccz .Lxb0_wdone
	s_sleep 3
	s_branch .Lxb0_wait
